# prep compression MLP: weight K-slices streamed by coalesced LDS-DMA into a per-wave 2-stage swizzled LDS ring, fragments read with ds_read_b128, activation fragments loaded once
# speedup vs baseline: 1.0351x; 1.0246x over previous
.LBB0_612:
	s_ashr_i32 s22, s28, 7
	s_bfe_u32 s35, s28, 0x20005
	s_cmpk_gt_u32 s28, 0x7f
	s_cselect_b64 s[20:21], -1, 0
	s_cmpk_lt_u32 s28, 0x80
	s_cselect_b64 s[24:25], -1, 0
	s_and_b64 s[0:1], s[24:25], exec
	s_movk_i32 s0, 0x880
	s_cselect_b32 s0, 0x800, s0
	s_lshl_b32 s1, s28, 1
	s_and_b32 s1, s1, 64
	s_or_b32 s4, s1, s0
	s_lshl_b32 s0, s28, 4
	s_and_b32 s34, s0, 0x1f0
	v_or_b32_e32 v0, s34, v139
	s_lshl_b32 s0, s28, 7
	v_lshlrev_b32_e32 v2, 4, v0
	v_mov_b32_e32 v3, 0x1fe0
	v_cmp_ne_u32_e32 vcc, s38, v0
	s_and_b32 s0, s0, 0x2000
	s_ashr_i32 s23, s22, 31
	v_cndmask_b32_e32 v0, v3, v2, vcc
	v_or_b32_e32 v0, s0, v0
	v_mul_u32_u24_e32 v0, 0x1320, v0
	v_lshlrev_b32_e32 v0, 1, v0
	v_lshl_add_u64 v[2:3], s[30:31], 0, v[0:1]
	s_lshl_b64 s[0:1], s[22:23], 20
	s_lshl_b32 s80, s4, 1
	v_lshl_add_u64 v[154:155], v[2:3], 0, s[80:81]
	v_lshl_add_u64 v[2:3], v[146:147], 0, s[0:1]
	v_lshl_add_u64 v[4:5], v[154:155], 0, s[14:15]
	v_lshlrev_b32_e32 v0, 1, v138
	v_lshl_add_u64 v[2:3], s[12:13], 1, v[2:3]
	v_lshl_add_u64 v[4:5], v[4:5], 0, v[0:1]
	v_lshl_add_u64 v[2:3], v[2:3], 0, v[0:1]
	s_waitcnt vmcnt(0) lgkmcnt(0)
	s_barrier
	v_readfirstlane_b32 s52, v2
	v_readfirstlane_b32 s53, v3
	v_readfirstlane_b32 s54, v4
	v_readfirstlane_b32 s55, v5
	s_lshl_b32 s58, s27, 14
	v_subrev_co_u32_e32 v221, vcc, s54, v4
	v_mov_b32_e32 v217, v221
	v_add_u32_e32 v218, 0x2640, v221
	v_add_u32_e32 v219, 0x4c80, v221
	v_add_u32_e32 v220, 0x72c0, v221
	global_load_dwordx4 v[66:69], v217, s[54:55]
	global_load_dwordx4 v[70:73], v217, s[54:55] offset:64
	global_load_dwordx4 v[74:77], v218, s[54:55]
	global_load_dwordx4 v[78:81], v218, s[54:55] offset:64
	global_load_dwordx4 v[82:85], v219, s[54:55]
	global_load_dwordx4 v[86:89], v219, s[54:55] offset:64
	global_load_dwordx4 v[90:93], v220, s[54:55]
	global_load_dwordx4 v[94:97], v220, s[54:55] offset:64
	v_lshrrev_b32_e32 v211, 5, v186
	v_and_b32_e32 v212, 31, v186
	v_add_u32_e32 v213, 0, v211
	v_xor_b32_e32 v214, v212, v213
	v_lshlrev_b32_e32 v214, 4, v214
	v_lshl_add_u32 v199, v213, 12, v214
	v_add_u32_e32 v213, 2, v211
	v_xor_b32_e32 v214, v212, v213
	v_lshlrev_b32_e32 v214, 4, v214
	v_lshl_add_u32 v200, v213, 12, v214
	v_add_u32_e32 v213, 4, v211
	v_xor_b32_e32 v214, v212, v213
	v_lshlrev_b32_e32 v214, 4, v214
	v_lshl_add_u32 v201, v213, 12, v214
	v_add_u32_e32 v213, 6, v211
	v_xor_b32_e32 v214, v212, v213
	v_lshlrev_b32_e32 v214, 4, v214
	v_lshl_add_u32 v202, v213, 12, v214
	v_add_u32_e32 v213, 8, v211
	v_xor_b32_e32 v214, v212, v213
	v_lshlrev_b32_e32 v214, 4, v214
	v_lshl_add_u32 v203, v213, 12, v214
	v_add_u32_e32 v213, 10, v211
	v_xor_b32_e32 v214, v212, v213
	v_lshlrev_b32_e32 v214, 4, v214
	v_lshl_add_u32 v204, v213, 12, v214
	v_add_u32_e32 v213, 12, v211
	v_xor_b32_e32 v214, v212, v213
	v_lshlrev_b32_e32 v214, 4, v214
	v_lshl_add_u32 v205, v213, 12, v214
	v_add_u32_e32 v213, 14, v211
	v_xor_b32_e32 v214, v212, v213
	v_lshlrev_b32_e32 v214, 4, v214
	v_lshl_add_u32 v206, v213, 12, v214
	v_and_b32_e32 v211, 15, v186
	v_lshrrev_b32_e32 v212, 4, v186
	v_xor_b32_e32 v213, v211, v212
	v_lshlrev_b32_e32 v214, 4, v213
	v_lshl_add_u32 v207, v211, 9, v214
	v_add_u32_e32 v207, s58, v207
	v_xor_b32_e32 v214, 4, v213
	v_lshlrev_b32_e32 v214, 4, v214
	v_lshl_add_u32 v208, v211, 9, v214
	v_add_u32_e32 v208, s58, v208
	v_xor_b32_e32 v214, 8, v213
	v_lshlrev_b32_e32 v214, 4, v214
	v_lshl_add_u32 v209, v211, 9, v214
	v_add_u32_e32 v209, s58, v209
	v_xor_b32_e32 v214, 12, v213
	v_lshlrev_b32_e32 v214, 4, v214
	v_lshl_add_u32 v210, v211, 9, v214
	v_add_u32_e32 v210, s58, v210
	s_mov_b32 s56, s52
	s_mov_b32 s57, s53
	s_add_u32 m0, s58, 0x0
	s_nop 0
	global_load_lds_dwordx4 v199, s[56:57]
	s_add_u32 m0, s58, 0x400
	s_nop 0
	global_load_lds_dwordx4 v200, s[56:57]
	s_add_u32 m0, s58, 0x800
	s_nop 0
	global_load_lds_dwordx4 v201, s[56:57]
	s_add_u32 m0, s58, 0xc00
	s_nop 0
	global_load_lds_dwordx4 v202, s[56:57]
	s_add_u32 m0, s58, 0x1000
	s_nop 0
	global_load_lds_dwordx4 v203, s[56:57]
	s_add_u32 m0, s58, 0x1400
	s_nop 0
	global_load_lds_dwordx4 v204, s[56:57]
	s_add_u32 m0, s58, 0x1800
	s_nop 0
	global_load_lds_dwordx4 v205, s[56:57]
	s_add_u32 m0, s58, 0x1c00
	s_nop 0
	global_load_lds_dwordx4 v206, s[56:57]
	s_add_u32 s56, s56, 0x10000
	s_addc_u32 s57, s57, 0
	s_add_u32 m0, s58, 0x2000
	s_nop 0
	global_load_lds_dwordx4 v199, s[56:57]
	s_add_u32 m0, s58, 0x2400
	s_nop 0
	global_load_lds_dwordx4 v200, s[56:57]
	s_add_u32 m0, s58, 0x2800
	s_nop 0
	global_load_lds_dwordx4 v201, s[56:57]
	s_add_u32 m0, s58, 0x2c00
	s_nop 0
	global_load_lds_dwordx4 v202, s[56:57]
	s_add_u32 m0, s58, 0x3000
	s_nop 0
	global_load_lds_dwordx4 v203, s[56:57]
	s_add_u32 m0, s58, 0x3400
	s_nop 0
	global_load_lds_dwordx4 v204, s[56:57]
	s_add_u32 m0, s58, 0x3800
	s_nop 0
	global_load_lds_dwordx4 v205, s[56:57]
	s_add_u32 m0, s58, 0x3c00
	s_nop 0
	global_load_lds_dwordx4 v206, s[56:57]
	s_waitcnt vmcnt(8)
	ds_read_b128 v[98:101], v207
	ds_read_b128 v[102:105], v208
	ds_read_b128 v[106:109], v209
	ds_read_b128 v[110:113], v210
	ds_read_b128 v[114:117], v207 offset:256
	ds_read_b128 v[118:121], v208 offset:256
	ds_read_b128 v[122:125], v209 offset:256
	ds_read_b128 v[126:129], v210 offset:256
	s_waitcnt lgkmcnt(0)
	s_add_u32 s56, s56, 0x10000
	s_addc_u32 s57, s57, 0
	s_add_u32 m0, s58, 0x0
	v_mfma_f32_16x16x32_bf16 v[30:33], v[66:69], v[98:101], 0
	global_load_lds_dwordx4 v199, s[56:57]
	s_add_u32 m0, s58, 0x400
	v_mfma_f32_16x16x32_bf16 v[30:33], v[70:73], v[102:105], v[30:33]
	global_load_lds_dwordx4 v200, s[56:57]
	s_add_u32 m0, s58, 0x800
	v_mfma_f32_16x16x32_bf16 v[30:33], v[74:77], v[106:109], v[30:33]
	global_load_lds_dwordx4 v201, s[56:57]
	s_add_u32 m0, s58, 0xc00
	v_mfma_f32_16x16x32_bf16 v[30:33], v[78:81], v[110:113], v[30:33]
	global_load_lds_dwordx4 v202, s[56:57]
	s_add_u32 m0, s58, 0x1000
	v_mfma_f32_16x16x32_bf16 v[30:33], v[82:85], v[114:117], v[30:33]
	global_load_lds_dwordx4 v203, s[56:57]
	s_add_u32 m0, s58, 0x1400
	v_mfma_f32_16x16x32_bf16 v[30:33], v[86:89], v[118:121], v[30:33]
	global_load_lds_dwordx4 v204, s[56:57]
	s_add_u32 m0, s58, 0x1800
	v_mfma_f32_16x16x32_bf16 v[30:33], v[90:93], v[122:125], v[30:33]
	global_load_lds_dwordx4 v205, s[56:57]
	s_add_u32 m0, s58, 0x1c00
	v_mfma_f32_16x16x32_bf16 v[30:33], v[94:97], v[126:129], v[30:33]
	global_load_lds_dwordx4 v206, s[56:57]
	s_waitcnt vmcnt(8)
	ds_read_b128 v[222:225], v207 offset:8192
	ds_read_b128 v[226:229], v208 offset:8192
	ds_read_b128 v[230:233], v209 offset:8192
	ds_read_b128 v[234:237], v210 offset:8192
	ds_read_b128 v[238:241], v207 offset:8448
	ds_read_b128 v[242:245], v208 offset:8448
	ds_read_b128 v[246:249], v209 offset:8448
	ds_read_b128 v[250:253], v210 offset:8448
	s_waitcnt lgkmcnt(0)
	s_add_u32 s56, s56, 0x10000
	s_addc_u32 s57, s57, 0
	s_add_u32 m0, s58, 0x2000
	v_mfma_f32_16x16x32_bf16 v[26:29], v[66:69], v[222:225], 0
	global_load_lds_dwordx4 v199, s[56:57]
	s_add_u32 m0, s58, 0x2400
	v_mfma_f32_16x16x32_bf16 v[26:29], v[70:73], v[226:229], v[26:29]
	global_load_lds_dwordx4 v200, s[56:57]
	s_add_u32 m0, s58, 0x2800
	v_mfma_f32_16x16x32_bf16 v[26:29], v[74:77], v[230:233], v[26:29]
	global_load_lds_dwordx4 v201, s[56:57]
	s_add_u32 m0, s58, 0x2c00
	v_mfma_f32_16x16x32_bf16 v[26:29], v[78:81], v[234:237], v[26:29]
	global_load_lds_dwordx4 v202, s[56:57]
	s_add_u32 m0, s58, 0x3000
	v_mfma_f32_16x16x32_bf16 v[26:29], v[82:85], v[238:241], v[26:29]
	global_load_lds_dwordx4 v203, s[56:57]
	s_add_u32 m0, s58, 0x3400
	v_mfma_f32_16x16x32_bf16 v[26:29], v[86:89], v[242:245], v[26:29]
	global_load_lds_dwordx4 v204, s[56:57]
	s_add_u32 m0, s58, 0x3800
	v_mfma_f32_16x16x32_bf16 v[26:29], v[90:93], v[246:249], v[26:29]
	global_load_lds_dwordx4 v205, s[56:57]
	s_add_u32 m0, s58, 0x3c00
	v_mfma_f32_16x16x32_bf16 v[26:29], v[94:97], v[250:253], v[26:29]
	global_load_lds_dwordx4 v206, s[56:57]
	s_waitcnt vmcnt(8)
	ds_read_b128 v[98:101], v207
	ds_read_b128 v[102:105], v208
	ds_read_b128 v[106:109], v209
	ds_read_b128 v[110:113], v210
	ds_read_b128 v[114:117], v207 offset:256
	ds_read_b128 v[118:121], v208 offset:256
	ds_read_b128 v[122:125], v209 offset:256
	ds_read_b128 v[126:129], v210 offset:256
	s_waitcnt lgkmcnt(0)
	s_add_u32 s56, s56, 0x10000
	s_addc_u32 s57, s57, 0
	s_add_u32 m0, s58, 0x0
	v_mfma_f32_16x16x32_bf16 v[22:25], v[66:69], v[98:101], 0
	global_load_lds_dwordx4 v199, s[56:57]
	s_add_u32 m0, s58, 0x400
	v_mfma_f32_16x16x32_bf16 v[22:25], v[70:73], v[102:105], v[22:25]
	global_load_lds_dwordx4 v200, s[56:57]
	s_add_u32 m0, s58, 0x800
	v_mfma_f32_16x16x32_bf16 v[22:25], v[74:77], v[106:109], v[22:25]
	global_load_lds_dwordx4 v201, s[56:57]
	s_add_u32 m0, s58, 0xc00
	v_mfma_f32_16x16x32_bf16 v[22:25], v[78:81], v[110:113], v[22:25]
	global_load_lds_dwordx4 v202, s[56:57]
	s_add_u32 m0, s58, 0x1000
	v_mfma_f32_16x16x32_bf16 v[22:25], v[82:85], v[114:117], v[22:25]
	global_load_lds_dwordx4 v203, s[56:57]
	s_add_u32 m0, s58, 0x1400
	v_mfma_f32_16x16x32_bf16 v[22:25], v[86:89], v[118:121], v[22:25]
	global_load_lds_dwordx4 v204, s[56:57]
	s_add_u32 m0, s58, 0x1800
	v_mfma_f32_16x16x32_bf16 v[22:25], v[90:93], v[122:125], v[22:25]
	global_load_lds_dwordx4 v205, s[56:57]
	s_add_u32 m0, s58, 0x1c00
	v_mfma_f32_16x16x32_bf16 v[22:25], v[94:97], v[126:129], v[22:25]
	global_load_lds_dwordx4 v206, s[56:57]
	s_waitcnt vmcnt(8)
	ds_read_b128 v[222:225], v207 offset:8192
	ds_read_b128 v[226:229], v208 offset:8192
	ds_read_b128 v[230:233], v209 offset:8192
	ds_read_b128 v[234:237], v210 offset:8192
	ds_read_b128 v[238:241], v207 offset:8448
	ds_read_b128 v[242:245], v208 offset:8448
	ds_read_b128 v[246:249], v209 offset:8448
	ds_read_b128 v[250:253], v210 offset:8448
	s_waitcnt lgkmcnt(0)
	s_add_u32 s56, s56, 0x10000
	s_addc_u32 s57, s57, 0
	s_add_u32 m0, s58, 0x2000
	v_mfma_f32_16x16x32_bf16 v[18:21], v[66:69], v[222:225], 0
	global_load_lds_dwordx4 v199, s[56:57]
	s_add_u32 m0, s58, 0x2400
	v_mfma_f32_16x16x32_bf16 v[18:21], v[70:73], v[226:229], v[18:21]
	global_load_lds_dwordx4 v200, s[56:57]
	s_add_u32 m0, s58, 0x2800
	v_mfma_f32_16x16x32_bf16 v[18:21], v[74:77], v[230:233], v[18:21]
	global_load_lds_dwordx4 v201, s[56:57]
	s_add_u32 m0, s58, 0x2c00
	v_mfma_f32_16x16x32_bf16 v[18:21], v[78:81], v[234:237], v[18:21]
	global_load_lds_dwordx4 v202, s[56:57]
	s_add_u32 m0, s58, 0x3000
	v_mfma_f32_16x16x32_bf16 v[18:21], v[82:85], v[238:241], v[18:21]
	global_load_lds_dwordx4 v203, s[56:57]
	s_add_u32 m0, s58, 0x3400
	v_mfma_f32_16x16x32_bf16 v[18:21], v[86:89], v[242:245], v[18:21]
	global_load_lds_dwordx4 v204, s[56:57]
	s_add_u32 m0, s58, 0x3800
	v_mfma_f32_16x16x32_bf16 v[18:21], v[90:93], v[246:249], v[18:21]
	global_load_lds_dwordx4 v205, s[56:57]
	s_add_u32 m0, s58, 0x3c00
	v_mfma_f32_16x16x32_bf16 v[18:21], v[94:97], v[250:253], v[18:21]
	global_load_lds_dwordx4 v206, s[56:57]
	s_waitcnt vmcnt(8)
	ds_read_b128 v[98:101], v207
	ds_read_b128 v[102:105], v208
	ds_read_b128 v[106:109], v209
	ds_read_b128 v[110:113], v210
	ds_read_b128 v[114:117], v207 offset:256
	ds_read_b128 v[118:121], v208 offset:256
	ds_read_b128 v[122:125], v209 offset:256
	ds_read_b128 v[126:129], v210 offset:256
	s_waitcnt lgkmcnt(0)
	s_add_u32 s56, s56, 0x10000
	s_addc_u32 s57, s57, 0
	s_add_u32 m0, s58, 0x0
	v_mfma_f32_16x16x32_bf16 v[14:17], v[66:69], v[98:101], 0
	global_load_lds_dwordx4 v199, s[56:57]
	s_add_u32 m0, s58, 0x400
	v_mfma_f32_16x16x32_bf16 v[14:17], v[70:73], v[102:105], v[14:17]
	global_load_lds_dwordx4 v200, s[56:57]
	s_add_u32 m0, s58, 0x800
	v_mfma_f32_16x16x32_bf16 v[14:17], v[74:77], v[106:109], v[14:17]
	global_load_lds_dwordx4 v201, s[56:57]
	s_add_u32 m0, s58, 0xc00
	v_mfma_f32_16x16x32_bf16 v[14:17], v[78:81], v[110:113], v[14:17]
	global_load_lds_dwordx4 v202, s[56:57]
	s_add_u32 m0, s58, 0x1000
	v_mfma_f32_16x16x32_bf16 v[14:17], v[82:85], v[114:117], v[14:17]
	global_load_lds_dwordx4 v203, s[56:57]
	s_add_u32 m0, s58, 0x1400
	v_mfma_f32_16x16x32_bf16 v[14:17], v[86:89], v[118:121], v[14:17]
	global_load_lds_dwordx4 v204, s[56:57]
	s_add_u32 m0, s58, 0x1800
	v_mfma_f32_16x16x32_bf16 v[14:17], v[90:93], v[122:125], v[14:17]
	global_load_lds_dwordx4 v205, s[56:57]
	s_add_u32 m0, s58, 0x1c00
	v_mfma_f32_16x16x32_bf16 v[14:17], v[94:97], v[126:129], v[14:17]
	global_load_lds_dwordx4 v206, s[56:57]
	s_waitcnt vmcnt(8)
	ds_read_b128 v[222:225], v207 offset:8192
	ds_read_b128 v[226:229], v208 offset:8192
	ds_read_b128 v[230:233], v209 offset:8192
	ds_read_b128 v[234:237], v210 offset:8192
	ds_read_b128 v[238:241], v207 offset:8448
	ds_read_b128 v[242:245], v208 offset:8448
	ds_read_b128 v[246:249], v209 offset:8448
	ds_read_b128 v[250:253], v210 offset:8448
	s_waitcnt lgkmcnt(0)
	s_add_u32 s56, s56, 0x10000
	s_addc_u32 s57, s57, 0
	s_add_u32 m0, s58, 0x2000
	v_mfma_f32_16x16x32_bf16 v[10:13], v[66:69], v[222:225], 0
	global_load_lds_dwordx4 v199, s[56:57]
	s_add_u32 m0, s58, 0x2400
	v_mfma_f32_16x16x32_bf16 v[10:13], v[70:73], v[226:229], v[10:13]
	global_load_lds_dwordx4 v200, s[56:57]
	s_add_u32 m0, s58, 0x2800
	v_mfma_f32_16x16x32_bf16 v[10:13], v[74:77], v[230:233], v[10:13]
	global_load_lds_dwordx4 v201, s[56:57]
	s_add_u32 m0, s58, 0x2c00
	v_mfma_f32_16x16x32_bf16 v[10:13], v[78:81], v[234:237], v[10:13]
	global_load_lds_dwordx4 v202, s[56:57]
	s_add_u32 m0, s58, 0x3000
	v_mfma_f32_16x16x32_bf16 v[10:13], v[82:85], v[238:241], v[10:13]
	global_load_lds_dwordx4 v203, s[56:57]
	s_add_u32 m0, s58, 0x3400
	v_mfma_f32_16x16x32_bf16 v[10:13], v[86:89], v[242:245], v[10:13]
	global_load_lds_dwordx4 v204, s[56:57]
	s_add_u32 m0, s58, 0x3800
	v_mfma_f32_16x16x32_bf16 v[10:13], v[90:93], v[246:249], v[10:13]
	global_load_lds_dwordx4 v205, s[56:57]
	s_add_u32 m0, s58, 0x3c00
	v_mfma_f32_16x16x32_bf16 v[10:13], v[94:97], v[250:253], v[10:13]
	global_load_lds_dwordx4 v206, s[56:57]
	s_waitcnt vmcnt(8)
	ds_read_b128 v[98:101], v207
	ds_read_b128 v[102:105], v208
	ds_read_b128 v[106:109], v209
	ds_read_b128 v[110:113], v210
	ds_read_b128 v[114:117], v207 offset:256
	ds_read_b128 v[118:121], v208 offset:256
	ds_read_b128 v[122:125], v209 offset:256
	ds_read_b128 v[126:129], v210 offset:256
	s_waitcnt lgkmcnt(0)
	s_add_u32 s56, s56, 0x10000
	s_addc_u32 s57, s57, 0
	s_add_u32 m0, s58, 0x0
	v_mfma_f32_16x16x32_bf16 v[6:9], v[66:69], v[98:101], 0
	global_load_lds_dwordx4 v199, s[56:57]
	s_add_u32 m0, s58, 0x400
	v_mfma_f32_16x16x32_bf16 v[6:9], v[70:73], v[102:105], v[6:9]
	global_load_lds_dwordx4 v200, s[56:57]
	s_add_u32 m0, s58, 0x800
	v_mfma_f32_16x16x32_bf16 v[6:9], v[74:77], v[106:109], v[6:9]
	global_load_lds_dwordx4 v201, s[56:57]
	s_add_u32 m0, s58, 0xc00
	v_mfma_f32_16x16x32_bf16 v[6:9], v[78:81], v[110:113], v[6:9]
	global_load_lds_dwordx4 v202, s[56:57]
	s_add_u32 m0, s58, 0x1000
	v_mfma_f32_16x16x32_bf16 v[6:9], v[82:85], v[114:117], v[6:9]
	global_load_lds_dwordx4 v203, s[56:57]
	s_add_u32 m0, s58, 0x1400
	v_mfma_f32_16x16x32_bf16 v[6:9], v[86:89], v[118:121], v[6:9]
	global_load_lds_dwordx4 v204, s[56:57]
	s_add_u32 m0, s58, 0x1800
	v_mfma_f32_16x16x32_bf16 v[6:9], v[90:93], v[122:125], v[6:9]
	global_load_lds_dwordx4 v205, s[56:57]
	s_add_u32 m0, s58, 0x1c00
	v_mfma_f32_16x16x32_bf16 v[6:9], v[94:97], v[126:129], v[6:9]
	global_load_lds_dwordx4 v206, s[56:57]
	s_waitcnt vmcnt(8)
	ds_read_b128 v[222:225], v207 offset:8192
	ds_read_b128 v[226:229], v208 offset:8192
	ds_read_b128 v[230:233], v209 offset:8192
	ds_read_b128 v[234:237], v210 offset:8192
	ds_read_b128 v[238:241], v207 offset:8448
	ds_read_b128 v[242:245], v208 offset:8448
	ds_read_b128 v[246:249], v209 offset:8448
	ds_read_b128 v[250:253], v210 offset:8448
	s_waitcnt lgkmcnt(0)
	s_add_u32 s56, s56, 0x10000
	s_addc_u32 s57, s57, 0
	s_add_u32 m0, s58, 0x2000
	v_mfma_f32_16x16x32_bf16 v[2:5], v[66:69], v[222:225], 0
	global_load_lds_dwordx4 v199, s[56:57]
	s_add_u32 m0, s58, 0x2400
	v_mfma_f32_16x16x32_bf16 v[2:5], v[70:73], v[226:229], v[2:5]
	global_load_lds_dwordx4 v200, s[56:57]
	s_add_u32 m0, s58, 0x2800
	v_mfma_f32_16x16x32_bf16 v[2:5], v[74:77], v[230:233], v[2:5]
	global_load_lds_dwordx4 v201, s[56:57]
	s_add_u32 m0, s58, 0x2c00
	v_mfma_f32_16x16x32_bf16 v[2:5], v[78:81], v[234:237], v[2:5]
	global_load_lds_dwordx4 v202, s[56:57]
	s_add_u32 m0, s58, 0x3000
	v_mfma_f32_16x16x32_bf16 v[2:5], v[82:85], v[238:241], v[2:5]
	global_load_lds_dwordx4 v203, s[56:57]
	s_add_u32 m0, s58, 0x3400
	v_mfma_f32_16x16x32_bf16 v[2:5], v[86:89], v[242:245], v[2:5]
	global_load_lds_dwordx4 v204, s[56:57]
	s_add_u32 m0, s58, 0x3800
	v_mfma_f32_16x16x32_bf16 v[2:5], v[90:93], v[246:249], v[2:5]
	global_load_lds_dwordx4 v205, s[56:57]
	s_add_u32 m0, s58, 0x3c00
	v_mfma_f32_16x16x32_bf16 v[2:5], v[94:97], v[250:253], v[2:5]
	global_load_lds_dwordx4 v206, s[56:57]
	s_waitcnt vmcnt(8)
	ds_read_b128 v[98:101], v207
	ds_read_b128 v[102:105], v208
	ds_read_b128 v[106:109], v209
	ds_read_b128 v[110:113], v210
	ds_read_b128 v[114:117], v207 offset:256
	ds_read_b128 v[118:121], v208 offset:256
	ds_read_b128 v[122:125], v209 offset:256
	ds_read_b128 v[126:129], v210 offset:256
	s_waitcnt lgkmcnt(0)
	s_add_u32 s56, s56, 0x10000
	s_addc_u32 s57, s57, 0
	s_add_u32 m0, s58, 0x0
	v_mfma_f32_16x16x32_bf16 v[34:37], v[66:69], v[98:101], 0
	global_load_lds_dwordx4 v199, s[56:57]
	s_add_u32 m0, s58, 0x400
	v_mfma_f32_16x16x32_bf16 v[34:37], v[70:73], v[102:105], v[34:37]
	global_load_lds_dwordx4 v200, s[56:57]
	s_add_u32 m0, s58, 0x800
	v_mfma_f32_16x16x32_bf16 v[34:37], v[74:77], v[106:109], v[34:37]
	global_load_lds_dwordx4 v201, s[56:57]
	s_add_u32 m0, s58, 0xc00
	v_mfma_f32_16x16x32_bf16 v[34:37], v[78:81], v[110:113], v[34:37]
	global_load_lds_dwordx4 v202, s[56:57]
	s_add_u32 m0, s58, 0x1000
	v_mfma_f32_16x16x32_bf16 v[34:37], v[82:85], v[114:117], v[34:37]
	global_load_lds_dwordx4 v203, s[56:57]
	s_add_u32 m0, s58, 0x1400
	v_mfma_f32_16x16x32_bf16 v[34:37], v[86:89], v[118:121], v[34:37]
	global_load_lds_dwordx4 v204, s[56:57]
	s_add_u32 m0, s58, 0x1800
	v_mfma_f32_16x16x32_bf16 v[34:37], v[90:93], v[122:125], v[34:37]
	global_load_lds_dwordx4 v205, s[56:57]
	s_add_u32 m0, s58, 0x1c00
	v_mfma_f32_16x16x32_bf16 v[34:37], v[94:97], v[126:129], v[34:37]
	global_load_lds_dwordx4 v206, s[56:57]
	s_waitcnt vmcnt(8)
	ds_read_b128 v[222:225], v207 offset:8192
	ds_read_b128 v[226:229], v208 offset:8192
	ds_read_b128 v[230:233], v209 offset:8192
	ds_read_b128 v[234:237], v210 offset:8192
	ds_read_b128 v[238:241], v207 offset:8448
	ds_read_b128 v[242:245], v208 offset:8448
	ds_read_b128 v[246:249], v209 offset:8448
	ds_read_b128 v[250:253], v210 offset:8448
	s_waitcnt lgkmcnt(0)
	s_add_u32 s56, s56, 0x10000
	s_addc_u32 s57, s57, 0
	s_add_u32 m0, s58, 0x2000
	v_mfma_f32_16x16x32_bf16 v[38:41], v[66:69], v[222:225], 0
	global_load_lds_dwordx4 v199, s[56:57]
	s_add_u32 m0, s58, 0x2400
	v_mfma_f32_16x16x32_bf16 v[38:41], v[70:73], v[226:229], v[38:41]
	global_load_lds_dwordx4 v200, s[56:57]
	s_add_u32 m0, s58, 0x2800
	v_mfma_f32_16x16x32_bf16 v[38:41], v[74:77], v[230:233], v[38:41]
	global_load_lds_dwordx4 v201, s[56:57]
	s_add_u32 m0, s58, 0x2c00
	v_mfma_f32_16x16x32_bf16 v[38:41], v[78:81], v[234:237], v[38:41]
	global_load_lds_dwordx4 v202, s[56:57]
	s_add_u32 m0, s58, 0x3000
	v_mfma_f32_16x16x32_bf16 v[38:41], v[82:85], v[238:241], v[38:41]
	global_load_lds_dwordx4 v203, s[56:57]
	s_add_u32 m0, s58, 0x3400
	v_mfma_f32_16x16x32_bf16 v[38:41], v[86:89], v[242:245], v[38:41]
	global_load_lds_dwordx4 v204, s[56:57]
	s_add_u32 m0, s58, 0x3800
	v_mfma_f32_16x16x32_bf16 v[38:41], v[90:93], v[246:249], v[38:41]
	global_load_lds_dwordx4 v205, s[56:57]
	s_add_u32 m0, s58, 0x3c00
	v_mfma_f32_16x16x32_bf16 v[38:41], v[94:97], v[250:253], v[38:41]
	global_load_lds_dwordx4 v206, s[56:57]
	s_waitcnt vmcnt(8)
	ds_read_b128 v[98:101], v207
	ds_read_b128 v[102:105], v208
	ds_read_b128 v[106:109], v209
	ds_read_b128 v[110:113], v210
	ds_read_b128 v[114:117], v207 offset:256
	ds_read_b128 v[118:121], v208 offset:256
	ds_read_b128 v[122:125], v209 offset:256
	ds_read_b128 v[126:129], v210 offset:256
	s_waitcnt lgkmcnt(0)
	s_add_u32 s56, s56, 0x10000
	s_addc_u32 s57, s57, 0
	s_add_u32 m0, s58, 0x0
	v_mfma_f32_16x16x32_bf16 v[42:45], v[66:69], v[98:101], 0
	global_load_lds_dwordx4 v199, s[56:57]
	s_add_u32 m0, s58, 0x400
	v_mfma_f32_16x16x32_bf16 v[42:45], v[70:73], v[102:105], v[42:45]
	global_load_lds_dwordx4 v200, s[56:57]
	s_add_u32 m0, s58, 0x800
	v_mfma_f32_16x16x32_bf16 v[42:45], v[74:77], v[106:109], v[42:45]
	global_load_lds_dwordx4 v201, s[56:57]
	s_add_u32 m0, s58, 0xc00
	v_mfma_f32_16x16x32_bf16 v[42:45], v[78:81], v[110:113], v[42:45]
	global_load_lds_dwordx4 v202, s[56:57]
	s_add_u32 m0, s58, 0x1000
	v_mfma_f32_16x16x32_bf16 v[42:45], v[82:85], v[114:117], v[42:45]
	global_load_lds_dwordx4 v203, s[56:57]
	s_add_u32 m0, s58, 0x1400
	v_mfma_f32_16x16x32_bf16 v[42:45], v[86:89], v[118:121], v[42:45]
	global_load_lds_dwordx4 v204, s[56:57]
	s_add_u32 m0, s58, 0x1800
	v_mfma_f32_16x16x32_bf16 v[42:45], v[90:93], v[122:125], v[42:45]
	global_load_lds_dwordx4 v205, s[56:57]
	s_add_u32 m0, s58, 0x1c00
	v_mfma_f32_16x16x32_bf16 v[42:45], v[94:97], v[126:129], v[42:45]
	global_load_lds_dwordx4 v206, s[56:57]
	s_waitcnt vmcnt(8)
	ds_read_b128 v[222:225], v207 offset:8192
	ds_read_b128 v[226:229], v208 offset:8192
	ds_read_b128 v[230:233], v209 offset:8192
	ds_read_b128 v[234:237], v210 offset:8192
	ds_read_b128 v[238:241], v207 offset:8448
	ds_read_b128 v[242:245], v208 offset:8448
	ds_read_b128 v[246:249], v209 offset:8448
	ds_read_b128 v[250:253], v210 offset:8448
	s_waitcnt lgkmcnt(0)
	s_add_u32 s56, s56, 0x10000
	s_addc_u32 s57, s57, 0
	s_add_u32 m0, s58, 0x2000
	v_mfma_f32_16x16x32_bf16 v[46:49], v[66:69], v[222:225], 0
	global_load_lds_dwordx4 v199, s[56:57]
	s_add_u32 m0, s58, 0x2400
	v_mfma_f32_16x16x32_bf16 v[46:49], v[70:73], v[226:229], v[46:49]
	global_load_lds_dwordx4 v200, s[56:57]
	s_add_u32 m0, s58, 0x2800
	v_mfma_f32_16x16x32_bf16 v[46:49], v[74:77], v[230:233], v[46:49]
	global_load_lds_dwordx4 v201, s[56:57]
	s_add_u32 m0, s58, 0x2c00
	v_mfma_f32_16x16x32_bf16 v[46:49], v[78:81], v[234:237], v[46:49]
	global_load_lds_dwordx4 v202, s[56:57]
	s_add_u32 m0, s58, 0x3000
	v_mfma_f32_16x16x32_bf16 v[46:49], v[82:85], v[238:241], v[46:49]
	global_load_lds_dwordx4 v203, s[56:57]
	s_add_u32 m0, s58, 0x3400
	v_mfma_f32_16x16x32_bf16 v[46:49], v[86:89], v[242:245], v[46:49]
	global_load_lds_dwordx4 v204, s[56:57]
	s_add_u32 m0, s58, 0x3800
	v_mfma_f32_16x16x32_bf16 v[46:49], v[90:93], v[246:249], v[46:49]
	global_load_lds_dwordx4 v205, s[56:57]
	s_add_u32 m0, s58, 0x3c00
	v_mfma_f32_16x16x32_bf16 v[46:49], v[94:97], v[250:253], v[46:49]
	global_load_lds_dwordx4 v206, s[56:57]
	s_waitcnt vmcnt(8)
	ds_read_b128 v[98:101], v207
	ds_read_b128 v[102:105], v208
	ds_read_b128 v[106:109], v209
	ds_read_b128 v[110:113], v210
	ds_read_b128 v[114:117], v207 offset:256
	ds_read_b128 v[118:121], v208 offset:256
	ds_read_b128 v[122:125], v209 offset:256
	ds_read_b128 v[126:129], v210 offset:256
	s_waitcnt lgkmcnt(0)
	s_add_u32 s56, s56, 0x10000
	s_addc_u32 s57, s57, 0
	s_add_u32 m0, s58, 0x0
	v_mfma_f32_16x16x32_bf16 v[50:53], v[66:69], v[98:101], 0
	global_load_lds_dwordx4 v199, s[56:57]
	s_add_u32 m0, s58, 0x400
	v_mfma_f32_16x16x32_bf16 v[50:53], v[70:73], v[102:105], v[50:53]
	global_load_lds_dwordx4 v200, s[56:57]
	s_add_u32 m0, s58, 0x800
	v_mfma_f32_16x16x32_bf16 v[50:53], v[74:77], v[106:109], v[50:53]
	global_load_lds_dwordx4 v201, s[56:57]
	s_add_u32 m0, s58, 0xc00
	v_mfma_f32_16x16x32_bf16 v[50:53], v[78:81], v[110:113], v[50:53]
	global_load_lds_dwordx4 v202, s[56:57]
	s_add_u32 m0, s58, 0x1000
	v_mfma_f32_16x16x32_bf16 v[50:53], v[82:85], v[114:117], v[50:53]
	global_load_lds_dwordx4 v203, s[56:57]
	s_add_u32 m0, s58, 0x1400
	v_mfma_f32_16x16x32_bf16 v[50:53], v[86:89], v[118:121], v[50:53]
	global_load_lds_dwordx4 v204, s[56:57]
	s_add_u32 m0, s58, 0x1800
	v_mfma_f32_16x16x32_bf16 v[50:53], v[90:93], v[122:125], v[50:53]
	global_load_lds_dwordx4 v205, s[56:57]
	s_add_u32 m0, s58, 0x1c00
	v_mfma_f32_16x16x32_bf16 v[50:53], v[94:97], v[126:129], v[50:53]
	global_load_lds_dwordx4 v206, s[56:57]
	s_waitcnt vmcnt(8)
	ds_read_b128 v[222:225], v207 offset:8192
	ds_read_b128 v[226:229], v208 offset:8192
	ds_read_b128 v[230:233], v209 offset:8192
	ds_read_b128 v[234:237], v210 offset:8192
	ds_read_b128 v[238:241], v207 offset:8448
	ds_read_b128 v[242:245], v208 offset:8448
	ds_read_b128 v[246:249], v209 offset:8448
	ds_read_b128 v[250:253], v210 offset:8448
	s_waitcnt lgkmcnt(0)
	s_add_u32 s56, s56, 0x10000
	s_addc_u32 s57, s57, 0
	s_add_u32 m0, s58, 0x2000
	v_mfma_f32_16x16x32_bf16 v[54:57], v[66:69], v[222:225], 0
	global_load_lds_dwordx4 v199, s[56:57]
	s_add_u32 m0, s58, 0x2400
	v_mfma_f32_16x16x32_bf16 v[54:57], v[70:73], v[226:229], v[54:57]
	global_load_lds_dwordx4 v200, s[56:57]
	s_add_u32 m0, s58, 0x2800
	v_mfma_f32_16x16x32_bf16 v[54:57], v[74:77], v[230:233], v[54:57]
	global_load_lds_dwordx4 v201, s[56:57]
	s_add_u32 m0, s58, 0x2c00
	v_mfma_f32_16x16x32_bf16 v[54:57], v[78:81], v[234:237], v[54:57]
	global_load_lds_dwordx4 v202, s[56:57]
	s_add_u32 m0, s58, 0x3000
	v_mfma_f32_16x16x32_bf16 v[54:57], v[82:85], v[238:241], v[54:57]
	global_load_lds_dwordx4 v203, s[56:57]
	s_add_u32 m0, s58, 0x3400
	v_mfma_f32_16x16x32_bf16 v[54:57], v[86:89], v[242:245], v[54:57]
	global_load_lds_dwordx4 v204, s[56:57]
	s_add_u32 m0, s58, 0x3800
	v_mfma_f32_16x16x32_bf16 v[54:57], v[90:93], v[246:249], v[54:57]
	global_load_lds_dwordx4 v205, s[56:57]
	s_add_u32 m0, s58, 0x3c00
	v_mfma_f32_16x16x32_bf16 v[54:57], v[94:97], v[250:253], v[54:57]
	global_load_lds_dwordx4 v206, s[56:57]
	s_waitcnt vmcnt(8)
	ds_read_b128 v[98:101], v207
	ds_read_b128 v[102:105], v208
	ds_read_b128 v[106:109], v209
	ds_read_b128 v[110:113], v210
	ds_read_b128 v[114:117], v207 offset:256
	ds_read_b128 v[118:121], v208 offset:256
	ds_read_b128 v[122:125], v209 offset:256
	ds_read_b128 v[126:129], v210 offset:256
	s_waitcnt lgkmcnt(0)
	v_mfma_f32_16x16x32_bf16 v[58:61], v[66:69], v[98:101], 0
	v_mfma_f32_16x16x32_bf16 v[58:61], v[70:73], v[102:105], v[58:61]
	v_mfma_f32_16x16x32_bf16 v[58:61], v[74:77], v[106:109], v[58:61]
	v_mfma_f32_16x16x32_bf16 v[58:61], v[78:81], v[110:113], v[58:61]
	v_mfma_f32_16x16x32_bf16 v[58:61], v[82:85], v[114:117], v[58:61]
	v_mfma_f32_16x16x32_bf16 v[58:61], v[86:89], v[118:121], v[58:61]
	v_mfma_f32_16x16x32_bf16 v[58:61], v[90:93], v[122:125], v[58:61]
	v_mfma_f32_16x16x32_bf16 v[58:61], v[94:97], v[126:129], v[58:61]
	s_waitcnt vmcnt(0)
	ds_read_b128 v[222:225], v207 offset:8192
	ds_read_b128 v[226:229], v208 offset:8192
	ds_read_b128 v[230:233], v209 offset:8192
	ds_read_b128 v[234:237], v210 offset:8192
	ds_read_b128 v[238:241], v207 offset:8448
	ds_read_b128 v[242:245], v208 offset:8448
	ds_read_b128 v[246:249], v209 offset:8448
	ds_read_b128 v[250:253], v210 offset:8448
	s_waitcnt lgkmcnt(0)
	v_mfma_f32_16x16x32_bf16 v[62:65], v[66:69], v[222:225], 0
	v_mfma_f32_16x16x32_bf16 v[62:65], v[70:73], v[226:229], v[62:65]
	v_mfma_f32_16x16x32_bf16 v[62:65], v[74:77], v[230:233], v[62:65]
	v_mfma_f32_16x16x32_bf16 v[62:65], v[78:81], v[234:237], v[62:65]
	v_mfma_f32_16x16x32_bf16 v[62:65], v[82:85], v[238:241], v[62:65]
	v_mfma_f32_16x16x32_bf16 v[62:65], v[86:89], v[242:245], v[62:65]
	v_mfma_f32_16x16x32_bf16 v[62:65], v[90:93], v[246:249], v[62:65]
	v_mfma_f32_16x16x32_bf16 v[62:65], v[94:97], v[250:253], v[62:65]
